# derived phase: serialized load-add chains (cmp bias sums, FoX cumsum) batched, bit-identical order
# speedup vs baseline: 1.0229x; 1.0013x over previous
; DEVI void phase_derived(const Params& p, int L, char* smem) {
;     ...
;       for (int i = 0; i < 64; ++i) s += flog[(long)(lane * 64 + i) * 4];
;       float incl = s;
; #pragma unroll
;       for (int off = 1; off < 64; off <<= 1) { float o = __shfl_up(incl, off); if (lane >= off) incl += o; }
;       float run = incl - s;
;       for (int i = 0; i < 64; ++i) { run += flog[(long)(lane * 64 + i) * 4]; cum[lane * 64 + i] = run * LOG2E; }
.LBB0_134:
	v_lshl_add_u64 v[8:9], v[6:7], 0, s[50:51]
	v_add_co_u32_e32 v8, vcc, 0x1b3bc000, v8
	s_add_u32 s50, s50, 0x100
	s_nop 0
	v_addc_co_u32_e32 v9, vcc, 0, v9, vcc
	flat_load_dword v236, v[8:9]
	flat_load_dword v237, v[8:9] offset:16
	flat_load_dword v238, v[8:9] offset:32
	flat_load_dword v239, v[8:9] offset:48
	flat_load_dword v240, v[8:9] offset:64
	flat_load_dword v241, v[8:9] offset:80
	flat_load_dword v242, v[8:9] offset:96
	flat_load_dword v243, v[8:9] offset:112
	flat_load_dword v244, v[8:9] offset:128
	flat_load_dword v245, v[8:9] offset:144
	flat_load_dword v246, v[8:9] offset:160
	flat_load_dword v247, v[8:9] offset:176
	flat_load_dword v230, v[8:9] offset:192
	flat_load_dword v231, v[8:9] offset:208
	flat_load_dword v218, v[8:9] offset:224
	flat_load_dword v219, v[8:9] offset:240
	s_waitcnt vmcnt(0) lgkmcnt(0)
	s_addc_u32 s51, s51, 0
	s_cmpk_eq_i32 s50, 0x400
	v_add_f32_e32 v0, v0, v236
	v_add_f32_e32 v0, v0, v237
	v_add_f32_e32 v0, v0, v238
	v_add_f32_e32 v0, v0, v239
	v_add_f32_e32 v0, v0, v240
	v_add_f32_e32 v0, v0, v241
	v_add_f32_e32 v0, v0, v242
	v_add_f32_e32 v0, v0, v243
	v_add_f32_e32 v0, v0, v244
	v_add_f32_e32 v0, v0, v245
	v_add_f32_e32 v0, v0, v246
	v_add_f32_e32 v0, v0, v247
	v_add_f32_e32 v0, v0, v230
	v_add_f32_e32 v0, v0, v231
	v_add_f32_e32 v0, v0, v218
	v_add_f32_e32 v0, v0, v219
	s_cbranch_scc0 .LBB0_134
	v_and_b32_e32 v5, 64, v184
	v_add_u32_e32 v6, -1, v184
	v_cmp_lt_i32_e32 vcc, v6, v5
	v_add_u32_e32 v7, -2, v184
	v_add_u32_e32 v8, -4, v184
	v_cndmask_b32_e32 v6, v6, v184, vcc
	v_lshlrev_b32_e32 v6, 2, v6
	ds_bpermute_b32 v6, v6, v0
	v_cmp_lt_i32_e32 vcc, v7, v5
	s_mov_b32 s6, 64
	v_lshl_add_u64 v[2:3], v[134:135], 0, v[2:3]
	v_cndmask_b32_e32 v7, v7, v184, vcc
	s_waitcnt lgkmcnt(0)
	v_add_f32_e32 v6, v0, v6
	v_cndmask_b32_e64 v6, v6, v0, s[60:61]
	v_lshlrev_b32_e32 v7, 2, v7
	ds_bpermute_b32 v7, v7, v6
	v_cmp_lt_i32_e32 vcc, v8, v5
	s_mov_b64 s[10:11], 0x80
	s_waitcnt lgkmcnt(0)
	v_add_f32_e32 v7, v6, v7
	v_cndmask_b32_e64 v6, v7, v6, s[70:71]
	v_cndmask_b32_e32 v7, v8, v184, vcc
	v_lshlrev_b32_e32 v7, 2, v7
	ds_bpermute_b32 v7, v7, v6
	v_add_u32_e32 v8, -8, v184
	v_cmp_lt_i32_e32 vcc, v8, v5
	s_waitcnt lgkmcnt(0)
	v_add_f32_e32 v7, v6, v7
	v_cndmask_b32_e64 v6, v7, v6, s[72:73]
	v_cndmask_b32_e32 v7, v8, v184, vcc
	v_lshlrev_b32_e32 v7, 2, v7
	ds_bpermute_b32 v7, v7, v6
	v_add_u32_e32 v8, -16, v184
	v_cmp_lt_i32_e32 vcc, v8, v5
	s_waitcnt lgkmcnt(0)
	v_add_f32_e32 v7, v6, v7
	v_cndmask_b32_e64 v6, v7, v6, s[74:75]
	v_cndmask_b32_e32 v7, v8, v184, vcc
	v_lshlrev_b32_e32 v7, 2, v7
	ds_bpermute_b32 v7, v7, v6
	v_subrev_u32_e32 v8, 32, v184
	v_cmp_lt_i32_e32 vcc, v8, v5
	s_waitcnt lgkmcnt(0)
	v_add_f32_e32 v7, v6, v7
	v_cndmask_b32_e32 v5, v8, v184, vcc
	v_cndmask_b32_e64 v6, v7, v6, s[38:39]
	v_lshlrev_b32_e32 v5, 2, v5
	ds_bpermute_b32 v7, v5, v6
	v_ashrrev_i32_e32 v5, 31, v4
	v_lshlrev_b64 v[4:5], 14, v[4:5]
	v_or_b32_e32 v4, v138, v4
	s_waitcnt lgkmcnt(0)
	v_add_f32_e32 v7, v6, v7
	v_cndmask_b32_e64 v6, v7, v6, s[40:41]
	v_sub_f32_e32 v0, v6, v0
.LBB0_136:
	v_lshl_add_u64 v[6:7], s[12:13], 0, v[2:3]
	v_add_co_u32_e32 v6, vcc, 0x1b3bc000, v6
	v_lshl_add_u64 v[8:9], s[12:13], 0, v[4:5]
	s_nop 0
	v_addc_co_u32_e32 v7, vcc, 0, v7, vcc
	flat_load_dword v236, v[6:7]
	flat_load_dword v237, v[6:7] offset:16
	flat_load_dword v238, v[6:7] offset:32
	flat_load_dword v239, v[6:7] offset:48
	flat_load_dword v240, v[6:7] offset:64
	flat_load_dword v241, v[6:7] offset:80
	flat_load_dword v242, v[6:7] offset:96
	flat_load_dword v243, v[6:7] offset:112
	s_waitcnt vmcnt(0) lgkmcnt(0)
	v_add_co_u32_e32 v8, vcc, 0x1b43c000, v8
	s_add_i32 s6, s6, -8
	s_nop 0
	v_addc_co_u32_e32 v9, vcc, 0, v9, vcc
	v_lshl_add_u64 v[4:5], v[4:5], 0, 32
	v_lshl_add_u64 v[2:3], v[2:3], 0, s[10:11]
	s_cmp_eq_u32 s6, 0
	v_add_f32_e32 v0, v0, v236
	v_mul_f32_e32 v10, 0x3fb8aa3b, v0
	flat_store_dword v[8:9], v10
	v_add_f32_e32 v0, v0, v237
	v_mul_f32_e32 v10, 0x3fb8aa3b, v0
	flat_store_dword v[8:9], v10 offset:4
	v_add_f32_e32 v0, v0, v238
	v_mul_f32_e32 v10, 0x3fb8aa3b, v0
	flat_store_dword v[8:9], v10 offset:8
	v_add_f32_e32 v0, v0, v239
	v_mul_f32_e32 v10, 0x3fb8aa3b, v0
	flat_store_dword v[8:9], v10 offset:12
	v_add_f32_e32 v0, v0, v240
	v_mul_f32_e32 v10, 0x3fb8aa3b, v0
	flat_store_dword v[8:9], v10 offset:16
	v_add_f32_e32 v0, v0, v241
	v_mul_f32_e32 v10, 0x3fb8aa3b, v0
	flat_store_dword v[8:9], v10 offset:20
	v_add_f32_e32 v0, v0, v242
	v_mul_f32_e32 v10, 0x3fb8aa3b, v0
	flat_store_dword v[8:9], v10 offset:24
	v_add_f32_e32 v0, v0, v243
	v_mul_f32_e32 v6, 0x3fb8aa3b, v0
	flat_store_dword v[8:9], v6 offset:28
	s_cbranch_scc0 .LBB0_136

; DEVI void phase_derived(const Params& p, int L, char* smem) {
;     ...
;         const int col = wc * 64 + n * 16 + fr;
;         float bb = 0.f;
; #pragma unroll 8
;         for (int ch = 0; ch < 32; ++ch) bb += b1[ch * 128 + col];
; #pragma unroll
;         for (int m = 0; m < 4; ++m)
; #pragma unroll
;           for (int j = 0; j < 4; ++j) Hs[(wr * 64 + m * 16 + fq * 4 + j) * 136 + col] = f2bf(gelu_tanh(acc[m][n][j] + bb));
.LBB0_170:
	v_lshl_add_u64 v[216:217], v[150:151], 0, s[54:55]
	v_add_co_u32_e32 v216, vcc, 0x22b4000, v216
	s_add_u32 s54, s54, 0x1000
	s_nop 0
	v_addc_co_u32_e32 v217, vcc, 0, v217, vcc
	flat_load_dword v236, v[216:217]
	flat_load_dword v237, v[216:217] offset:512
	flat_load_dword v238, v[216:217] offset:1024
	flat_load_dword v239, v[216:217] offset:1536
	flat_load_dword v240, v[216:217] offset:2048
	flat_load_dword v241, v[216:217] offset:2560
	flat_load_dword v242, v[216:217] offset:3072
	flat_load_dword v243, v[216:217] offset:3584
	s_waitcnt vmcnt(0) lgkmcnt(0)
	s_addc_u32 s55, s55, 0
	s_cmpk_eq_i32 s54, 0x4000
	v_add_f32_e32 v0, v0, v236
	v_add_f32_e32 v0, v0, v237
	v_add_f32_e32 v0, v0, v238
	v_add_f32_e32 v0, v0, v239
	v_add_f32_e32 v0, v0, v240
	v_add_f32_e32 v0, v0, v241
	v_add_f32_e32 v0, v0, v242
	v_add_f32_e32 v0, v0, v243
	s_cbranch_scc0 .LBB0_170
	v_mfma_f32_16x16x32_bf16 v[46:49], v[94:97], v[70:73], v[46:49]
	v_add_f32_e32 v62, v62, v0
	v_mfma_f32_16x16x32_bf16 v[42:45], v[94:97], v[66:69], v[42:45]
	v_mfma_f32_16x16x32_bf16 v[38:41], v[86:89], v[70:73], v[38:41]
	v_mfma_f32_16x16x32_bf16 v[34:37], v[86:89], v[66:69], v[34:37]
	v_mfma_f32_16x16x32_bf16 v[86:89], v[82:85], v[70:73], v[14:17]
	v_mfma_f32_16x16x32_bf16 v[82:85], v[82:85], v[66:69], v[10:13]
	v_mfma_f32_16x16x32_bf16 v[70:73], v[74:77], v[70:73], v[6:9]
	v_mfma_f32_16x16x32_bf16 v[2:5], v[74:77], v[66:69], v[2:5]
	v_mul_f32_e32 v66, 0x3d372713, v62
	v_mul_f32_e32 v66, v62, v66
	v_fma_f32 v66, v62, v66, v62
	v_mfma_f32_16x16x32_bf16 v[46:49], v[110:113], v[98:101], v[46:49]
	v_mul_f32_e32 v66, 0x3f4c422a, v66
	v_cmp_nlt_f32_e64 s[6:7], |v66|, s34
	v_mfma_f32_16x16x32_bf16 v[14:17], v[110:113], v[90:93], v[42:45]
	v_mfma_f32_16x16x32_bf16 v[42:45], v[106:109], v[98:101], v[38:41]
	v_mfma_f32_16x16x32_bf16 v[10:13], v[106:109], v[90:93], v[34:37]
	v_mfma_f32_16x16x32_bf16 v[38:41], v[102:105], v[98:101], v[86:89]
	v_mfma_f32_16x16x32_bf16 v[6:9], v[102:105], v[90:93], v[82:85]
	v_mfma_f32_16x16x32_bf16 v[34:37], v[78:81], v[98:101], v[70:73]
	v_mfma_f32_16x16x32_bf16 v[2:5], v[78:81], v[90:93], v[2:5]
	s_and_saveexec_b64 s[54:55], s[6:7]
	s_xor_b64 s[6:7], exec, s[54:55]
	s_cbranch_execz .LBB0_173
	v_add_f32_e64 v67, |v66|, |v66|
	v_mul_f32_e32 v68, 0x3fb8aa3b, v67
	v_rndne_f32_e32 v69, v68
	v_sub_f32_e32 v70, v68, v69
	v_fma_f32 v68, v67, s58, -v68
	v_fmac_f32_e32 v68, 0x32a5705f, v67
	v_add_f32_e32 v68, v70, v68
	v_cvt_i32_f32_e32 v69, v69
	v_exp_f32_e32 v68, v68
	v_cmp_ngt_f32_e32 vcc, s84, v67
	v_ldexp_f32 v68, v68, v69
	s_nop 0
	v_cndmask_b32_e32 v68, 0, v68, vcc
	v_cmp_nlt_f32_e32 vcc, s47, v67
	s_nop 1
	v_cndmask_b32_e32 v67, v179, v68, vcc
	v_add_f32_e32 v67, 1.0, v67
	v_rcp_f32_e32 v67, v67
	s_nop 0
	v_fma_f32 v67, v67, -2.0, 1.0

; DEVI void phase_derived(const Params& p, int L, char* smem) {
;     ...
;         const int col = wc * 64 + n * 16 + fr;
;         float bb = 0.f;
; #pragma unroll 8
;         for (int ch = 0; ch < 32; ++ch) bb += b1[ch * 128 + col];
; #pragma unroll
;         for (int m = 0; m < 4; ++m)
; #pragma unroll
;           for (int j = 0; j < 4; ++j) Hs[(wr * 64 + m * 16 + fq * 4 + j) * 136 + col] = f2bf(gelu_tanh(acc[m][n][j] + bb));
.LBB0_236:
	v_lshl_add_u64 v[50:51], v[150:151], 0, s[54:55]
	v_add_co_u32_e32 v50, vcc, 0x22b4000, v50
	s_add_u32 s54, s54, 0x1000
	s_nop 0
	v_addc_co_u32_e32 v51, vcc, 0, v51, vcc
	flat_load_dword v236, v[50:51] offset:64
	flat_load_dword v237, v[50:51] offset:576
	flat_load_dword v238, v[50:51] offset:1088
	flat_load_dword v239, v[50:51] offset:1600
	flat_load_dword v240, v[50:51] offset:2112
	flat_load_dword v241, v[50:51] offset:2624
	flat_load_dword v242, v[50:51] offset:3136
	flat_load_dword v243, v[50:51] offset:3648
	s_waitcnt vmcnt(0) lgkmcnt(0)
	s_addc_u32 s55, s55, 0
	s_cmpk_lg_i32 s54, 0x4000
	v_add_f32_e32 v0, v0, v236
	v_add_f32_e32 v0, v0, v237
	v_add_f32_e32 v0, v0, v238
	v_add_f32_e32 v0, v0, v239
	v_add_f32_e32 v0, v0, v240
	v_add_f32_e32 v0, v0, v241
	v_add_f32_e32 v0, v0, v242
	v_add_f32_e32 v0, v0, v243
	s_cbranch_scc1 .LBB0_236
	v_add_f32_e32 v46, v46, v0
	v_mul_f32_e32 v50, 0x3d372713, v46
	v_mul_f32_e32 v50, v46, v50
	v_fma_f32 v50, v46, v50, v46
	v_mul_f32_e32 v50, 0x3f4c422a, v50
	v_cmp_nlt_f32_e64 s[6:7], |v50|, s34
	s_and_saveexec_b64 s[54:55], s[6:7]
	s_xor_b64 s[6:7], exec, s[54:55]
	s_cbranch_execz .LBB0_239
	v_add_f32_e64 v51, |v50|, |v50|
	v_mul_f32_e32 v52, 0x3fb8aa3b, v51
	v_rndne_f32_e32 v53, v52
	v_sub_f32_e32 v54, v52, v53
	v_fma_f32 v52, v51, s58, -v52
	v_fmac_f32_e32 v52, 0x32a5705f, v51
	v_add_f32_e32 v52, v54, v52
	v_cvt_i32_f32_e32 v53, v53
	v_exp_f32_e32 v52, v52
	v_cmp_ngt_f32_e32 vcc, s84, v51
	v_ldexp_f32 v52, v52, v53
	s_nop 0
	v_cndmask_b32_e32 v52, 0, v52, vcc
	v_cmp_nlt_f32_e32 vcc, s47, v51
	s_nop 1
	v_cndmask_b32_e32 v51, v179, v52, vcc
	v_add_f32_e32 v51, 1.0, v51
	v_rcp_f32_e32 v51, v51
	s_nop 0
	v_fma_f32 v51, v51, -2.0, 1.0

; DEVI void phase_derived(const Params& p, int L, char* smem) {
;     ...
;         const int col = wc * 64 + n * 16 + fr;
;         float bb = 0.f;
; #pragma unroll 8
;         for (int ch = 0; ch < 32; ++ch) bb += b1[ch * 128 + col];
; #pragma unroll
;         for (int m = 0; m < 4; ++m)
; #pragma unroll
;           for (int j = 0; j < 4; ++j) Hs[(wr * 64 + m * 16 + fq * 4 + j) * 136 + col] = f2bf(gelu_tanh(acc[m][n][j] + bb));
.LBB0_302:
	v_lshl_add_u64 v[34:35], v[150:151], 0, s[54:55]
	v_add_co_u32_e32 v34, vcc, 0x22b4000, v34
	s_add_u32 s54, s54, 0x1000
	s_nop 0
	v_addc_co_u32_e32 v35, vcc, 0, v35, vcc
	flat_load_dword v236, v[34:35] offset:128
	flat_load_dword v237, v[34:35] offset:640
	flat_load_dword v238, v[34:35] offset:1152
	flat_load_dword v239, v[34:35] offset:1664
	flat_load_dword v240, v[34:35] offset:2176
	flat_load_dword v241, v[34:35] offset:2688
	flat_load_dword v242, v[34:35] offset:3200
	flat_load_dword v243, v[34:35] offset:3712
	s_waitcnt vmcnt(0) lgkmcnt(0)
	s_addc_u32 s55, s55, 0
	s_cmpk_lg_i32 s54, 0x4000
	v_add_f32_e32 v0, v0, v236
	v_add_f32_e32 v0, v0, v237
	v_add_f32_e32 v0, v0, v238
	v_add_f32_e32 v0, v0, v239
	v_add_f32_e32 v0, v0, v240
	v_add_f32_e32 v0, v0, v241
	v_add_f32_e32 v0, v0, v242
	v_add_f32_e32 v0, v0, v243
	s_cbranch_scc1 .LBB0_302
	v_add_f32_e32 v30, v30, v0
	v_mul_f32_e32 v34, 0x3d372713, v30
	v_mul_f32_e32 v34, v30, v34
	v_fma_f32 v34, v30, v34, v30
	v_mul_f32_e32 v34, 0x3f4c422a, v34
	v_cmp_nlt_f32_e64 s[6:7], |v34|, s34
	s_and_saveexec_b64 s[54:55], s[6:7]
	s_xor_b64 s[6:7], exec, s[54:55]
	s_cbranch_execz .LBB0_305
	v_add_f32_e64 v35, |v34|, |v34|
	v_mul_f32_e32 v36, 0x3fb8aa3b, v35
	v_rndne_f32_e32 v37, v36
	v_sub_f32_e32 v38, v36, v37
	v_fma_f32 v36, v35, s58, -v36
	v_fmac_f32_e32 v36, 0x32a5705f, v35
	v_add_f32_e32 v36, v38, v36
	v_cvt_i32_f32_e32 v37, v37
	v_exp_f32_e32 v36, v36
	v_cmp_ngt_f32_e32 vcc, s84, v35
	v_ldexp_f32 v36, v36, v37
	s_nop 0
	v_cndmask_b32_e32 v36, 0, v36, vcc
	v_cmp_nlt_f32_e32 vcc, s47, v35
	s_nop 1
	v_cndmask_b32_e32 v35, v179, v36, vcc
	v_add_f32_e32 v35, 1.0, v35
	v_rcp_f32_e32 v35, v35
	s_nop 0
	v_fma_f32 v35, v35, -2.0, 1.0

; DEVI void phase_derived(const Params& p, int L, char* smem) {
;     ...
;         const int col = wc * 64 + n * 16 + fr;
;         float bb = 0.f;
; #pragma unroll 8
;         for (int ch = 0; ch < 32; ++ch) bb += b1[ch * 128 + col];
; #pragma unroll
;         for (int m = 0; m < 4; ++m)
; #pragma unroll
;           for (int j = 0; j < 4; ++j) Hs[(wr * 64 + m * 16 + fq * 4 + j) * 136 + col] = f2bf(gelu_tanh(acc[m][n][j] + bb));
.LBB0_368:
	v_lshl_add_u64 v[18:19], v[150:151], 0, s[54:55]
	v_add_co_u32_e32 v18, vcc, 0x22b4000, v18
	s_add_u32 s54, s54, 0x1000
	s_nop 0
	v_addc_co_u32_e32 v19, vcc, 0, v19, vcc
	flat_load_dword v236, v[18:19] offset:192
	flat_load_dword v237, v[18:19] offset:704
	flat_load_dword v238, v[18:19] offset:1216
	flat_load_dword v239, v[18:19] offset:1728
	flat_load_dword v240, v[18:19] offset:2240
	flat_load_dword v241, v[18:19] offset:2752
	flat_load_dword v242, v[18:19] offset:3264
	flat_load_dword v243, v[18:19] offset:3776
	s_waitcnt vmcnt(0) lgkmcnt(0)
	s_addc_u32 s55, s55, 0
	s_cmpk_lg_i32 s54, 0x4000
	v_add_f32_e32 v0, v0, v236
	v_add_f32_e32 v0, v0, v237
	v_add_f32_e32 v0, v0, v238
	v_add_f32_e32 v0, v0, v239
	v_add_f32_e32 v0, v0, v240
	v_add_f32_e32 v0, v0, v241
	v_add_f32_e32 v0, v0, v242
	v_add_f32_e32 v0, v0, v243
	s_cbranch_scc1 .LBB0_368
	v_add_f32_e32 v14, v14, v0
	v_mul_f32_e32 v18, 0x3d372713, v14
	v_mul_f32_e32 v18, v14, v18
	v_fma_f32 v18, v14, v18, v14
	v_mul_f32_e32 v18, 0x3f4c422a, v18
	v_cmp_nlt_f32_e64 s[6:7], |v18|, s34
	s_and_saveexec_b64 s[54:55], s[6:7]
	s_xor_b64 s[6:7], exec, s[54:55]
	s_cbranch_execz .LBB0_371
	v_add_f32_e64 v19, |v18|, |v18|
	v_mul_f32_e32 v20, 0x3fb8aa3b, v19
	v_rndne_f32_e32 v21, v20
	v_sub_f32_e32 v22, v20, v21
	v_fma_f32 v20, v19, s58, -v20
	v_fmac_f32_e32 v20, 0x32a5705f, v19
	v_add_f32_e32 v20, v22, v20
	v_cvt_i32_f32_e32 v21, v21
	v_exp_f32_e32 v20, v20
	v_cmp_ngt_f32_e32 vcc, s84, v19
	v_ldexp_f32 v20, v20, v21
	s_nop 0
	v_cndmask_b32_e32 v20, 0, v20, vcc
	v_cmp_nlt_f32_e32 vcc, s47, v19
	s_nop 1
	v_cndmask_b32_e32 v19, v179, v20, vcc
	v_add_f32_e32 v19, 1.0, v19
	v_rcp_f32_e32 v19, v19
	s_nop 0
	v_fma_f32 v19, v19, -2.0, 1.0
